# GEMM unit scheduler: shift/mask fast path when the M-group size is 8 (skips the rcp-based division) in all 14 scheduler instances
# speedup vs baseline: 1.0076x; 1.0025x over previous
.LBB0_419:
	v_readlane_b32 s2, v249, 30
	s_lshl_b32 s2, s2, 3
	s_abs_i32 s3, s2
	v_cvt_f32_u32_e32 v0, s3
	s_sub_i32 s9, 0, s3
	s_ashr_i32 s1, s1, 3
	s_add_i32 s1, s6, s1
	v_rcp_iflag_f32_e32 v0, v0
	s_abs_i32 s7, s1
	s_xor_b32 s6, s1, s2
	s_ashr_i32 s6, s6, 31
	v_mul_f32_e32 v0, 0x4f7ffffe, v0
	v_cvt_u32_f32_e32 v0, v0
	s_nop 0
	v_readfirstlane_b32 s13, v0
	s_mul_i32 s9, s9, s13
	s_mul_hi_u32 s9, s13, s9
	s_add_i32 s13, s13, s9
	s_mul_hi_u32 s9, s7, s13
	s_mul_i32 s13, s9, s3
	s_sub_i32 s7, s7, s13
	s_add_i32 s21, s9, 1
	s_sub_i32 s13, s7, s3
	s_cmp_ge_u32 s7, s3
	s_cselect_b32 s9, s21, s9
	s_cselect_b32 s7, s13, s7
	s_add_i32 s13, s9, 1
	s_cmp_ge_u32 s7, s3
	s_cselect_b32 s3, s13, s9
	s_xor_b32 s3, s3, s6
	s_sub_i32 s3, s3, s6
	s_lshl_b32 s6, s3, 3
	s_sub_i32 s7, s73, s6
	s_min_i32 s7, s7, 8
	s_cmp_lg_u32 s7, 8
	s_cbranch_scc1 .Lsn_slow_0
	s_mul_i32 s3, s3, s2
	s_sub_i32 s1, s1, s3
	s_and_b32 s98, s1, 7
	s_ashr_i32 s95, s1, 3
	s_add_i32 s50, s98, s6
	s_branch .Lsn_join_0
.Lsn_slow_0:
	s_abs_i32 s9, s7
	v_cvt_f32_u32_e32 v0, s9
	s_sub_i32 s13, 0, s9
	s_mul_i32 s3, s3, s2
	s_sub_i32 s1, s1, s3
	v_rcp_iflag_f32_e32 v0, v0
	s_abs_i32 s2, s1
	s_xor_b32 s3, s1, s7
	s_ashr_i32 s3, s3, 31
	v_mul_f32_e32 v0, 0x4f7ffffe, v0
	v_cvt_u32_f32_e32 v0, v0
	s_nop 0
	v_readfirstlane_b32 s21, v0
	s_mul_i32 s13, s13, s21
	s_mul_hi_u32 s13, s21, s13
	s_add_i32 s21, s21, s13
	s_mul_hi_u32 s13, s2, s21
	s_mul_i32 s21, s13, s9
	s_sub_i32 s2, s2, s21
	s_add_i32 s23, s13, 1
	s_sub_i32 s21, s2, s9
	s_cmp_ge_u32 s2, s9
	s_cselect_b32 s13, s23, s13
	s_cselect_b32 s2, s21, s2
	s_add_i32 s21, s13, 1
	s_cmp_ge_u32 s2, s9
	s_cselect_b32 s2, s21, s13
	s_xor_b32 s2, s2, s3
	s_sub_i32 s95, s2, s3
	s_mul_i32 s2, s95, s7
	s_sub_i32 s1, s1, s2
	s_add_i32 s50, s1, s6
.Lsn_join_0:
	v_readlane_b32 s1, v249, 38
	s_cmp_lg_u32 s1, 2
	s_mov_b64 s[6:7], -1
	s_cbranch_scc0 .LBB0_421
	v_readlane_b32 s1, v249, 18
	s_mul_hi_i32 s3, s50, s1
	s_mul_i32 s2, s50, s1
	s_mov_b64 s[6:7], 0

.LBB0_443:
	s_ashr_i32 s5, s5, 3
	s_add_i32 s5, s9, s5
	s_abs_i32 s7, s5
	s_mul_hi_u32 s8, s7, s89
	s_mul_i32 s9, s8, s87
	s_ashr_i32 s6, s5, 31
	s_sub_i32 s7, s7, s9
	s_xor_b32 s6, s6, s86
	s_add_i32 s9, s8, 1
	s_sub_i32 s33, s7, s87
	s_cmp_ge_u32 s7, s87
	s_cselect_b32 s8, s9, s8
	s_cselect_b32 s7, s33, s7
	s_add_i32 s9, s8, 1
	s_cmp_ge_u32 s7, s87
	s_cselect_b32 s7, s9, s8
	s_xor_b32 s7, s7, s6
	s_sub_i32 s6, s7, s6
	s_lshl_b32 s7, s6, 3
	s_sub_i32 s8, s73, s7
	s_min_i32 s8, s8, 8
	s_cmp_lg_u32 s8, 8
	s_cbranch_scc1 .Lsn_slow_1
	s_mul_i32 s6, s6, s85
	s_sub_i32 s5, s5, s6
	s_and_b32 s98, s5, 7
	s_ashr_i32 s93, s5, 3
	s_add_i32 s94, s98, s7
	s_branch .Lsn_join_1
.Lsn_slow_1:
	s_abs_i32 s33, s8
	v_cvt_f32_u32_e32 v0, s33
	s_sub_i32 s36, 0, s33
	s_mul_i32 s6, s6, s85
	s_sub_i32 s5, s5, s6
	v_rcp_iflag_f32_e32 v0, v0
	s_abs_i32 s9, s5
	s_xor_b32 s6, s5, s8
	s_ashr_i32 s6, s6, 31
	v_mul_f32_e32 v0, 0x4f7ffffe, v0
	v_cvt_u32_f32_e32 v0, v0
	s_nop 0
	v_readfirstlane_b32 s37, v0
	s_mul_i32 s36, s36, s37
	s_mul_hi_u32 s36, s37, s36
	s_add_i32 s37, s37, s36
	s_mul_hi_u32 s36, s9, s37
	s_mul_i32 s37, s36, s33
	s_sub_i32 s9, s9, s37
	s_add_i32 s37, s36, 1
	s_sub_i32 s46, s9, s33
	s_cmp_ge_u32 s9, s33
	s_cselect_b32 s36, s37, s36
	s_cselect_b32 s9, s46, s9
	s_add_i32 s37, s36, 1
	s_cmp_ge_u32 s9, s33
	s_cselect_b32 s9, s37, s36
	s_xor_b32 s9, s9, s6
	s_sub_i32 s93, s9, s6
	s_mul_i32 s6, s93, s8
	s_sub_i32 s5, s5, s6
	s_add_i32 s94, s5, s7
.Lsn_join_1:
	s_mov_b64 s[36:37], -1
	s_and_b64 vcc, exec, s[40:41]
	s_cbranch_vccz .LBB0_447
	v_readlane_b32 s5, v249, 18
	s_mul_hi_i32 s7, s94, s5
	s_mul_i32 s6, s94, s5
	s_cbranch_execz .LBB0_448

.LBB0_493:
	s_ashr_i32 s2, s4, 3
	v_readlane_b32 s4, v249, 30
	s_lshl_b32 s52, s4, 3
	s_abs_i32 s55, s52
	v_cvt_f32_u32_e32 v0, s55
	s_sub_i32 s5, 0, s55
	s_add_i32 s2, s8, s2
	s_bfe_i32 s53, s4, 0x1001c
	v_rcp_iflag_f32_e32 v0, v0
	s_abs_i32 s4, s2
	s_ashr_i32 s3, s2, 31
	s_xor_b32 s3, s3, s53
	v_mul_f32_e32 v0, 0x4f7ffffe, v0
	v_cvt_u32_f32_e32 v0, v0
	s_nop 0
	v_readfirstlane_b32 s78, v0
	s_mul_i32 s5, s5, s78
	s_mul_hi_u32 s5, s78, s5
	s_add_i32 s78, s78, s5
	s_mul_hi_u32 s5, s4, s78
	s_mul_i32 s8, s5, s55
	s_sub_i32 s4, s4, s8
	s_add_i32 s8, s5, 1
	s_sub_i32 s21, s4, s55
	s_cmp_ge_u32 s4, s55
	s_cselect_b32 s5, s8, s5
	s_cselect_b32 s4, s21, s4
	s_add_i32 s8, s5, 1
	s_cmp_ge_u32 s4, s55
	s_cselect_b32 s4, s8, s5
	s_xor_b32 s4, s4, s3
	s_sub_i32 s3, s4, s3
	s_lshl_b32 s4, s3, 3
	s_sub_i32 s5, s73, s4
	s_min_i32 s5, s5, 8
	s_cmp_lg_u32 s5, 8
	s_cbranch_scc1 .Lsn_slow_2
	s_mul_i32 s3, s3, s52
	s_sub_i32 s2, s2, s3
	s_and_b32 s98, s2, 7
	s_ashr_i32 s8, s2, 3
	s_add_i32 s21, s98, s4
	s_branch .Lsn_join_2
.Lsn_slow_2:
	s_abs_i32 s21, s5
	v_cvt_f32_u32_e32 v0, s21
	s_sub_i32 s28, 0, s21
	s_mul_i32 s3, s3, s52
	s_sub_i32 s2, s2, s3
	v_rcp_iflag_f32_e32 v0, v0
	s_abs_i32 s8, s2
	s_xor_b32 s3, s2, s5
	s_ashr_i32 s3, s3, 31
	v_mul_f32_e32 v0, 0x4f7ffffe, v0
	v_cvt_u32_f32_e32 v0, v0
	s_nop 0
	v_readfirstlane_b32 s29, v0
	s_mul_i32 s28, s28, s29
	s_mul_hi_u32 s28, s29, s28
	s_add_i32 s29, s29, s28
	s_mul_hi_u32 s28, s8, s29
	s_mul_i32 s29, s28, s21
	s_sub_i32 s8, s8, s29
	s_add_i32 s29, s28, 1
	s_sub_i32 s30, s8, s21
	s_cmp_ge_u32 s8, s21
	s_cselect_b32 s28, s29, s28
	s_cselect_b32 s8, s30, s8
	s_add_i32 s29, s28, 1
	s_cmp_ge_u32 s8, s21
	s_cselect_b32 s8, s29, s28
	s_xor_b32 s8, s8, s3
	s_sub_i32 s8, s8, s3
	s_mul_i32 s3, s8, s5
	s_sub_i32 s21, s2, s3
	s_add_i32 s21, s21, s4
.Lsn_join_2:
	v_readlane_b32 s2, v249, 38
	s_cmp_lg_u32 s2, 2
	s_cselect_b64 s[28:29], -1, 0
	s_mov_b64 s[4:5], -1
	s_and_b64 vcc, exec, s[28:29]
	s_cbranch_vccz .LBB0_495
	v_readlane_b32 s2, v249, 18
	s_mul_hi_i32 s3, s21, s2
	s_mul_i32 s2, s21, s2
	s_mov_b64 s[4:5], 0

.LBB0_516:
	s_ashr_i32 s0, s3, 3
	s_add_i32 s0, s33, s0
	s_abs_i32 s3, s0
	s_mul_hi_u32 s9, s3, s78
	s_mul_i32 s33, s9, s55
	s_ashr_i32 s1, s0, 31
	s_sub_i32 s3, s3, s33
	s_xor_b32 s1, s1, s53
	s_add_i32 s33, s9, 1
	s_sub_i32 s46, s3, s55
	s_cmp_ge_u32 s3, s55
	s_cselect_b32 s9, s33, s9
	s_cselect_b32 s3, s46, s3
	s_add_i32 s33, s9, 1
	s_cmp_ge_u32 s3, s55
	s_cselect_b32 s3, s33, s9
	s_xor_b32 s3, s3, s1
	s_sub_i32 s1, s3, s1
	s_lshl_b32 s3, s1, 3
	s_sub_i32 s9, s73, s3
	s_min_i32 s9, s9, 8
	s_cmp_lg_u32 s9, 8
	s_cbranch_scc1 .Lsn_slow_3
	s_mul_i32 s1, s1, s52
	s_sub_i32 s0, s0, s1
	s_and_b32 s98, s0, 7
	s_ashr_i32 s95, s0, 3
	s_add_i32 s9, s98, s3
	s_branch .Lsn_join_3
.Lsn_slow_3:
	s_abs_i32 s46, s9
	v_cvt_f32_u32_e32 v0, s46
	s_sub_i32 s47, 0, s46
	s_mul_i32 s1, s1, s52
	s_sub_i32 s0, s0, s1
	v_rcp_iflag_f32_e32 v0, v0
	s_abs_i32 s33, s0
	s_xor_b32 s1, s0, s9
	s_ashr_i32 s1, s1, 31
	v_mul_f32_e32 v0, 0x4f7ffffe, v0
	v_cvt_u32_f32_e32 v0, v0
	s_nop 0
	v_readfirstlane_b32 s48, v0
	s_mul_i32 s47, s47, s48
	s_mul_hi_u32 s47, s48, s47
	s_add_i32 s48, s48, s47
	s_mul_hi_u32 s47, s33, s48
	s_mul_i32 s48, s47, s46
	s_sub_i32 s33, s33, s48
	s_add_i32 s48, s47, 1
	s_sub_i32 s49, s33, s46
	s_cmp_ge_u32 s33, s46
	s_cselect_b32 s47, s48, s47
	s_cselect_b32 s33, s49, s33
	s_add_i32 s48, s47, 1
	s_cmp_ge_u32 s33, s46
	s_cselect_b32 s33, s48, s47
	s_xor_b32 s33, s33, s1
	s_sub_i32 s95, s33, s1
	s_mul_i32 s1, s95, s9
	s_sub_i32 s9, s0, s1
	s_add_i32 s9, s9, s3
.Lsn_join_3:
	s_mov_b64 s[46:47], -1
	s_and_b64 vcc, exec, s[28:29]
	s_cbranch_vccz .LBB0_520
	v_readlane_b32 s0, v249, 18
	s_mul_hi_i32 s1, s9, s0
	s_mul_i32 s0, s9, s0
	s_cbranch_execz .LBB0_521

.LBB0_548:
	s_ashr_i32 s2, s4, 3
	v_readlane_b32 s4, v249, 30
	s_lshl_b32 s79, s4, 3
	s_abs_i32 s81, s79
	v_cvt_f32_u32_e32 v0, s81
	s_sub_i32 s5, 0, s81
	s_add_i32 s2, s6, s2
	s_bfe_i32 s80, s4, 0x1001c
	v_rcp_iflag_f32_e32 v0, v0
	s_abs_i32 s4, s2
	s_ashr_i32 s3, s2, 31
	s_xor_b32 s3, s3, s80
	v_mul_f32_e32 v0, 0x4f7ffffe, v0
	v_cvt_u32_f32_e32 v0, v0
	s_nop 0
	v_readfirstlane_b32 s82, v0
	s_mul_i32 s5, s5, s82
	s_mul_hi_u32 s5, s82, s5
	s_add_i32 s82, s82, s5
	s_mul_hi_u32 s5, s4, s82
	s_mul_i32 s6, s5, s81
	s_sub_i32 s4, s4, s6
	s_add_i32 s6, s5, 1
	s_sub_i32 s7, s4, s81
	s_cmp_ge_u32 s4, s81
	s_cselect_b32 s5, s6, s5
	s_cselect_b32 s4, s7, s4
	s_add_i32 s6, s5, 1
	s_cmp_ge_u32 s4, s81
	s_cselect_b32 s4, s6, s5
	s_xor_b32 s4, s4, s3
	s_sub_i32 s3, s4, s3
	s_lshl_b32 s4, s3, 3
	s_sub_i32 s5, s73, s4
	s_min_i32 s5, s5, 8
	s_cmp_lg_u32 s5, 8
	s_cbranch_scc1 .Lsn_slow_4
	s_mul_i32 s3, s3, s79
	s_sub_i32 s2, s2, s3
	s_and_b32 s98, s2, 7
	s_ashr_i32 s40, s2, 3
	s_add_i32 s42, s98, s4
	s_branch .Lsn_join_4
.Lsn_slow_4:
	s_abs_i32 s7, s5
	v_cvt_f32_u32_e32 v0, s7
	s_sub_i32 s9, 0, s7
	s_mul_i32 s3, s3, s79
	s_sub_i32 s2, s2, s3
	v_rcp_iflag_f32_e32 v0, v0
	s_abs_i32 s6, s2
	s_xor_b32 s3, s2, s5
	s_ashr_i32 s3, s3, 31
	v_mul_f32_e32 v0, 0x4f7ffffe, v0
	v_cvt_u32_f32_e32 v0, v0
	s_nop 0
	v_readfirstlane_b32 s23, v0
	s_mul_i32 s9, s9, s23
	s_mul_hi_u32 s9, s23, s9
	s_add_i32 s23, s23, s9
	s_mul_hi_u32 s9, s6, s23
	s_mul_i32 s23, s9, s7
	s_sub_i32 s6, s6, s23
	s_add_i32 s23, s9, 1
	s_sub_i32 s30, s6, s7
	s_cmp_ge_u32 s6, s7
	s_cselect_b32 s9, s23, s9
	s_cselect_b32 s6, s30, s6
	s_add_i32 s23, s9, 1
	s_cmp_ge_u32 s6, s7
	s_cselect_b32 s6, s23, s9
	s_xor_b32 s6, s6, s3
	s_sub_i32 s40, s6, s3
	s_mul_i32 s3, s40, s5
	s_sub_i32 s2, s2, s3
	s_add_i32 s42, s2, s4
.Lsn_join_4:
	v_readlane_b32 s2, v249, 38
	s_cmp_lg_u32 s2, 2
	s_cselect_b64 s[30:31], -1, 0
	s_mov_b64 s[4:5], -1
	s_and_b64 vcc, exec, s[30:31]
	s_cbranch_vccz .LBB0_550
	v_readlane_b32 s2, v249, 18
	s_mul_hi_i32 s3, s42, s2
	s_mul_i32 s2, s42, s2
	s_mov_b64 s[4:5], 0

.LBB0_571:
	s_ashr_i32 s8, s8, 3
	s_add_i32 s8, s41, s8
	s_abs_i32 s41, s8
	s_mul_hi_u32 s43, s41, s82
	s_mul_i32 s44, s43, s81
	s_ashr_i32 s9, s8, 31
	s_sub_i32 s41, s41, s44
	s_xor_b32 s9, s9, s80
	s_add_i32 s44, s43, 1
	s_sub_i32 s45, s41, s81
	s_cmp_ge_u32 s41, s81
	s_cselect_b32 s43, s44, s43
	s_cselect_b32 s41, s45, s41
	s_add_i32 s44, s43, 1
	s_cmp_ge_u32 s41, s81
	s_cselect_b32 s41, s44, s43
	s_xor_b32 s41, s41, s9
	s_sub_i32 s9, s41, s9
	s_lshl_b32 s41, s9, 3
	s_sub_i32 s43, s73, s41
	s_min_i32 s43, s43, 8
	s_cmp_lg_u32 s43, 8
	s_cbranch_scc1 .Lsn_slow_5
	s_mul_i32 s9, s9, s79
	s_sub_i32 s9, s8, s9
	s_and_b32 s98, s9, 7
	s_ashr_i32 s8, s9, 3
	s_add_i32 s9, s98, s41
	s_branch .Lsn_join_5
.Lsn_slow_5:
	s_abs_i32 s45, s43
	v_cvt_f32_u32_e32 v0, s45
	s_sub_i32 s47, 0, s45
	s_mul_i32 s9, s9, s79
	s_sub_i32 s9, s8, s9
	v_rcp_iflag_f32_e32 v0, v0
	s_abs_i32 s44, s9
	s_xor_b32 s8, s9, s43
	s_ashr_i32 s8, s8, 31
	v_mul_f32_e32 v0, 0x4f7ffffe, v0
	v_cvt_u32_f32_e32 v0, v0
	s_nop 0
	v_readfirstlane_b32 s50, v0
	s_mul_i32 s47, s47, s50
	s_mul_hi_u32 s47, s50, s47
	s_add_i32 s50, s50, s47
	s_mul_hi_u32 s47, s44, s50
	s_mul_i32 s50, s47, s45
	s_sub_i32 s44, s44, s50
	s_add_i32 s50, s47, 1
	s_sub_i32 s51, s44, s45
	s_cmp_ge_u32 s44, s45
	s_cselect_b32 s47, s50, s47
	s_cselect_b32 s44, s51, s44
	s_add_i32 s50, s47, 1
	s_cmp_ge_u32 s44, s45
	s_cselect_b32 s44, s50, s47
	s_xor_b32 s44, s44, s8
	s_sub_i32 s8, s44, s8
	s_mul_i32 s43, s8, s43
	s_sub_i32 s9, s9, s43
	s_add_i32 s9, s9, s41
.Lsn_join_5:
	s_mov_b64 s[50:51], -1
	s_and_b64 vcc, exec, s[30:31]
	s_cbranch_vccz .LBB0_575
	v_readlane_b32 s41, v249, 18
	s_mul_hi_i32 s45, s9, s41
	s_mul_i32 s44, s9, s41
	s_cbranch_execz .LBB0_576

.LBB0_600:
	v_readlane_b32 s0, v249, 30
	s_lshl_b32 s0, s0, 3
	s_abs_i32 s1, s0
	v_cvt_f32_u32_e32 v0, s1
	s_sub_i32 s9, 0, s1
	s_ashr_i32 s2, s2, 3
	s_add_i32 s2, s3, s2
	v_rcp_iflag_f32_e32 v0, v0
	s_abs_i32 s7, s2
	s_xor_b32 s3, s2, s0
	s_ashr_i32 s3, s3, 31
	v_mul_f32_e32 v0, 0x4f7ffffe, v0
	v_cvt_u32_f32_e32 v0, v0
	s_mov_b64 s[30:31], -1
	v_readfirstlane_b32 s13, v0
	s_mul_i32 s9, s9, s13
	s_mul_hi_u32 s9, s13, s9
	s_add_i32 s13, s13, s9
	s_mul_hi_u32 s9, s7, s13
	s_mul_i32 s13, s9, s1
	s_sub_i32 s7, s7, s13
	s_add_i32 s21, s9, 1
	s_sub_i32 s13, s7, s1
	s_cmp_ge_u32 s7, s1
	s_cselect_b32 s9, s21, s9
	s_cselect_b32 s7, s13, s7
	s_add_i32 s13, s9, 1
	s_cmp_ge_u32 s7, s1
	s_cselect_b32 s1, s13, s9
	s_xor_b32 s1, s1, s3
	s_sub_i32 s1, s1, s3
	s_lshl_b32 s3, s1, 3
	s_sub_i32 s7, s73, s3
	s_min_i32 s7, s7, 8
	s_cmp_lg_u32 s7, 8
	s_cbranch_scc1 .Lsn_slow_6
	s_mul_i32 s1, s1, s0
	s_sub_i32 s0, s2, s1
	s_and_b32 s98, s0, 7
	s_ashr_i32 s96, s0, 3
	s_add_i32 s0, s98, s3
	s_branch .Lsn_join_6
.Lsn_slow_6:
	s_abs_i32 s9, s7
	v_cvt_f32_u32_e32 v0, s9
	s_sub_i32 s13, 0, s9
	s_mul_i32 s1, s1, s0
	s_sub_i32 s0, s2, s1
	v_rcp_iflag_f32_e32 v0, v0
	s_abs_i32 s1, s0
	s_xor_b32 s2, s0, s7
	s_ashr_i32 s2, s2, 31
	v_mul_f32_e32 v0, 0x4f7ffffe, v0
	v_cvt_u32_f32_e32 v0, v0
	s_nop 0
	v_readfirstlane_b32 s21, v0
	s_mul_i32 s13, s13, s21
	s_mul_hi_u32 s13, s21, s13
	s_add_i32 s21, s21, s13
	s_mul_hi_u32 s13, s1, s21
	s_mul_i32 s21, s13, s9
	s_sub_i32 s1, s1, s21
	s_add_i32 s23, s13, 1
	s_sub_i32 s21, s1, s9
	s_cmp_ge_u32 s1, s9
	s_cselect_b32 s13, s23, s13
	s_cselect_b32 s1, s21, s1
	s_add_i32 s21, s13, 1
	s_cmp_ge_u32 s1, s9
	s_cselect_b32 s1, s21, s13
	s_xor_b32 s1, s1, s2
	s_sub_i32 s96, s1, s2
	s_mul_i32 s1, s96, s7
	s_sub_i32 s0, s0, s1
	s_add_i32 s0, s0, s3
.Lsn_join_6:
	v_readlane_b32 s1, v249, 38
	s_cmp_lg_u32 s1, 2
	s_cbranch_scc0 .LBB0_602
	v_readlane_b32 s1, v249, 18
	s_mul_hi_i32 s3, s0, s1
	s_mul_i32 s2, s0, s1
	s_mov_b64 s[30:31], 0

.LBB0_624:
	s_ashr_i32 s1, s1, 3
	s_add_i32 s1, s8, s1
	s_abs_i32 s8, s1
	s_mul_hi_u32 s9, s8, s93
	s_mul_i32 s33, s9, s89
	s_ashr_i32 s5, s1, 31
	s_sub_i32 s8, s8, s33
	s_xor_b32 s5, s5, s90
	s_add_i32 s33, s9, 1
	s_sub_i32 s36, s8, s89
	s_cmp_ge_u32 s8, s89
	s_cselect_b32 s9, s33, s9
	s_cselect_b32 s8, s36, s8
	s_add_i32 s33, s9, 1
	s_cmp_ge_u32 s8, s89
	s_cselect_b32 s8, s33, s9
	s_xor_b32 s8, s8, s5
	s_sub_i32 s5, s8, s5
	s_lshl_b32 s8, s5, 3
	s_sub_i32 s9, s73, s8
	s_min_i32 s9, s9, 8
	s_cmp_lg_u32 s9, 8
	s_cbranch_scc1 .Lsn_slow_7
	s_mul_i32 s5, s5, s66
	s_sub_i32 s1, s1, s5
	s_and_b32 s98, s1, 7
	s_ashr_i32 s55, s1, 3
	s_add_i32 s97, s98, s8
	s_branch .Lsn_join_7
.Lsn_slow_7:
	s_abs_i32 s36, s9
	v_cvt_f32_u32_e32 v0, s36
	s_sub_i32 s37, 0, s36
	s_mul_i32 s5, s5, s66
	s_sub_i32 s1, s1, s5
	v_rcp_iflag_f32_e32 v0, v0
	s_abs_i32 s33, s1
	s_xor_b32 s5, s1, s9
	s_ashr_i32 s5, s5, 31
	v_mul_f32_e32 v0, 0x4f7ffffe, v0
	v_cvt_u32_f32_e32 v0, v0
	s_nop 0
	v_readfirstlane_b32 s48, v0
	s_mul_i32 s37, s37, s48
	s_mul_hi_u32 s37, s48, s37
	s_add_i32 s48, s48, s37
	s_mul_hi_u32 s37, s33, s48
	s_mul_i32 s48, s37, s36
	s_sub_i32 s33, s33, s48
	s_add_i32 s48, s37, 1
	s_sub_i32 s49, s33, s36
	s_cmp_ge_u32 s33, s36
	s_cselect_b32 s37, s48, s37
	s_cselect_b32 s33, s49, s33
	s_add_i32 s48, s37, 1
	s_cmp_ge_u32 s33, s36
	s_cselect_b32 s33, s48, s37
	s_xor_b32 s33, s33, s5
	s_sub_i32 s55, s33, s5
	s_mul_i32 s5, s55, s9
	s_sub_i32 s1, s1, s5
	s_add_i32 s97, s1, s8
.Lsn_join_7:
	s_mov_b64 s[48:49], -1
	s_and_b64 vcc, exec, s[40:41]
	s_cbranch_vccz .LBB0_628
	v_readlane_b32 s1, v249, 18
	s_mul_hi_i32 s37, s97, s1
	s_mul_i32 s36, s97, s1
	s_cbranch_execz .LBB0_629

.LBB0_975:
	v_readlane_b32 s2, v249, 30
	s_lshl_b32 s2, s2, 3
	s_abs_i32 s3, s2
	v_cvt_f32_u32_e32 v0, s3
	s_sub_i32 s9, 0, s3
	s_ashr_i32 s1, s1, 3
	s_add_i32 s1, s6, s1
	v_rcp_iflag_f32_e32 v0, v0
	s_abs_i32 s7, s1
	s_xor_b32 s6, s1, s2
	s_ashr_i32 s6, s6, 31
	v_mul_f32_e32 v0, 0x4f7ffffe, v0
	v_cvt_u32_f32_e32 v0, v0
	s_nop 0
	v_readfirstlane_b32 s13, v0
	s_mul_i32 s9, s9, s13
	s_mul_hi_u32 s9, s13, s9
	s_add_i32 s13, s13, s9
	s_mul_hi_u32 s9, s7, s13
	s_mul_i32 s13, s9, s3
	s_sub_i32 s7, s7, s13
	s_add_i32 s21, s9, 1
	s_sub_i32 s13, s7, s3
	s_cmp_ge_u32 s7, s3
	s_cselect_b32 s9, s21, s9
	s_cselect_b32 s7, s13, s7
	s_add_i32 s13, s9, 1
	s_cmp_ge_u32 s7, s3
	s_cselect_b32 s3, s13, s9
	s_xor_b32 s3, s3, s6
	s_sub_i32 s3, s3, s6
	s_lshl_b32 s6, s3, 3
	s_sub_i32 s7, s73, s6
	s_min_i32 s7, s7, 8
	s_cmp_lg_u32 s7, 8
	s_cbranch_scc1 .Lsn_slow_8
	s_mul_i32 s3, s3, s2
	s_sub_i32 s1, s1, s3
	s_and_b32 s98, s1, 7
	s_ashr_i32 s30, s1, 3
	s_add_i32 s34, s98, s6
	s_branch .Lsn_join_8
.Lsn_slow_8:
	s_abs_i32 s9, s7
	v_cvt_f32_u32_e32 v0, s9
	s_sub_i32 s13, 0, s9
	s_mul_i32 s3, s3, s2
	s_sub_i32 s1, s1, s3
	v_rcp_iflag_f32_e32 v0, v0
	s_abs_i32 s2, s1
	s_xor_b32 s3, s1, s7
	s_ashr_i32 s3, s3, 31
	v_mul_f32_e32 v0, 0x4f7ffffe, v0
	v_cvt_u32_f32_e32 v0, v0
	s_nop 0
	v_readfirstlane_b32 s21, v0
	s_mul_i32 s13, s13, s21
	s_mul_hi_u32 s13, s21, s13
	s_add_i32 s21, s21, s13
	s_mul_hi_u32 s13, s2, s21
	s_mul_i32 s21, s13, s9
	s_sub_i32 s2, s2, s21
	s_add_i32 s23, s13, 1
	s_sub_i32 s21, s2, s9
	s_cmp_ge_u32 s2, s9
	s_cselect_b32 s13, s23, s13
	s_cselect_b32 s2, s21, s2
	s_add_i32 s21, s13, 1
	s_cmp_ge_u32 s2, s9
	s_cselect_b32 s2, s21, s13
	s_xor_b32 s2, s2, s3
	s_sub_i32 s30, s2, s3
	s_mul_i32 s2, s30, s7
	s_sub_i32 s1, s1, s2
	s_add_i32 s34, s1, s6
.Lsn_join_8:
	v_readlane_b32 s1, v249, 38
	s_cmp_lg_u32 s1, 2
	s_mov_b64 s[6:7], -1
	s_cbranch_scc0 .LBB0_977
	v_readlane_b32 s1, v249, 18
	s_mul_hi_i32 s3, s34, s1
	s_mul_i32 s2, s34, s1
	s_mov_b64 s[6:7], 0

.LBB0_999:
	s_ashr_i32 s0, s3, 3
	s_add_i32 s0, s9, s0
	s_abs_i32 s3, s0
	s_mul_hi_u32 s8, s3, s91
	s_mul_i32 s9, s8, s89
	s_ashr_i32 s1, s0, 31
	s_sub_i32 s3, s3, s9
	s_xor_b32 s1, s1, s88
	s_add_i32 s9, s8, 1
	s_sub_i32 s31, s3, s89
	s_cmp_ge_u32 s3, s89
	s_cselect_b32 s8, s9, s8
	s_cselect_b32 s3, s31, s3
	s_add_i32 s9, s8, 1
	s_cmp_ge_u32 s3, s89
	s_cselect_b32 s3, s9, s8
	s_xor_b32 s3, s3, s1
	s_sub_i32 s1, s3, s1
	s_lshl_b32 s3, s1, 3
	s_sub_i32 s8, s73, s3
	s_min_i32 s8, s8, 8
	s_cmp_lg_u32 s8, 8
	s_cbranch_scc1 .Lsn_slow_9
	s_mul_i32 s1, s1, s87
	s_sub_i32 s0, s0, s1
	s_and_b32 s98, s0, 7
	s_ashr_i32 s54, s0, 3
	s_add_i32 s95, s98, s3
	s_branch .Lsn_join_9
.Lsn_slow_9:
	s_abs_i32 s31, s8
	v_cvt_f32_u32_e32 v0, s31
	s_sub_i32 s35, 0, s31
	s_mul_i32 s1, s1, s87
	s_sub_i32 s0, s0, s1
	v_rcp_iflag_f32_e32 v0, v0
	s_abs_i32 s9, s0
	s_xor_b32 s1, s0, s8
	s_ashr_i32 s1, s1, 31
	v_mul_f32_e32 v0, 0x4f7ffffe, v0
	v_cvt_u32_f32_e32 v0, v0
	s_nop 0
	v_readfirstlane_b32 s50, v0
	s_mul_i32 s35, s35, s50
	s_mul_hi_u32 s35, s50, s35
	s_add_i32 s50, s50, s35
	s_mul_hi_u32 s35, s9, s50
	s_mul_i32 s50, s35, s31
	s_sub_i32 s9, s9, s50
	s_add_i32 s50, s35, 1
	s_sub_i32 s51, s9, s31
	s_cmp_ge_u32 s9, s31
	s_cselect_b32 s35, s50, s35
	s_cselect_b32 s9, s51, s9
	s_add_i32 s50, s35, 1
	s_cmp_ge_u32 s9, s31
	s_cselect_b32 s9, s50, s35
	s_xor_b32 s9, s9, s1
	s_sub_i32 s54, s9, s1
	s_mul_i32 s1, s54, s8
	s_sub_i32 s0, s0, s1
	s_add_i32 s95, s0, s3
.Lsn_join_9:
	s_mov_b64 s[50:51], -1
	s_and_b64 vcc, exec, s[42:43]
	s_cbranch_vccz .LBB0_1003
	v_readlane_b32 s0, v249, 18
	s_mul_hi_i32 s1, s95, s0
	s_mul_i32 s0, s95, s0
	s_cbranch_execz .LBB0_1004

.LBB0_1050:
	s_ashr_i32 s2, s4, 3
	v_readlane_b32 s4, v249, 30
	s_lshl_b32 s51, s4, 3
	s_abs_i32 s53, s51
	v_cvt_f32_u32_e32 v0, s53
	s_sub_i32 s5, 0, s53
	s_add_i32 s2, s8, s2
	s_bfe_i32 s52, s4, 0x1001c
	v_rcp_iflag_f32_e32 v0, v0
	s_abs_i32 s4, s2
	s_ashr_i32 s3, s2, 31
	s_xor_b32 s3, s3, s52
	v_mul_f32_e32 v0, 0x4f7ffffe, v0
	v_cvt_u32_f32_e32 v0, v0
	s_nop 0
	v_readfirstlane_b32 s55, v0
	s_mul_i32 s5, s5, s55
	s_mul_hi_u32 s5, s55, s5
	s_add_i32 s55, s55, s5
	s_mul_hi_u32 s5, s4, s55
	s_mul_i32 s8, s5, s53
	s_sub_i32 s4, s4, s8
	s_add_i32 s8, s5, 1
	s_sub_i32 s28, s4, s53
	s_cmp_ge_u32 s4, s53
	s_cselect_b32 s5, s8, s5
	s_cselect_b32 s4, s28, s4
	s_add_i32 s8, s5, 1
	s_cmp_ge_u32 s4, s53
	s_cselect_b32 s4, s8, s5
	s_xor_b32 s4, s4, s3
	s_sub_i32 s3, s4, s3
	s_lshl_b32 s4, s3, 3
	s_sub_i32 s5, s73, s4
	s_min_i32 s5, s5, 8
	s_cmp_lg_u32 s5, 8
	s_cbranch_scc1 .Lsn_slow_10
	s_mul_i32 s3, s3, s51
	s_sub_i32 s2, s2, s3
	s_and_b32 s98, s2, 7
	s_ashr_i32 s33, s2, 3
	s_add_i32 s8, s98, s4
	s_branch .Lsn_join_10
.Lsn_slow_10:
	s_abs_i32 s28, s5
	v_cvt_f32_u32_e32 v0, s28
	s_sub_i32 s29, 0, s28
	s_mul_i32 s3, s3, s51
	s_sub_i32 s2, s2, s3
	v_rcp_iflag_f32_e32 v0, v0
	s_abs_i32 s8, s2
	s_xor_b32 s3, s2, s5
	s_ashr_i32 s3, s3, 31
	v_mul_f32_e32 v0, 0x4f7ffffe, v0
	v_cvt_u32_f32_e32 v0, v0
	s_nop 0
	v_readfirstlane_b32 s30, v0
	s_mul_i32 s29, s29, s30
	s_mul_hi_u32 s29, s30, s29
	s_add_i32 s30, s30, s29
	s_mul_hi_u32 s29, s8, s30
	s_mul_i32 s30, s29, s28
	s_sub_i32 s8, s8, s30
	s_add_i32 s30, s29, 1
	s_sub_i32 s31, s8, s28
	s_cmp_ge_u32 s8, s28
	s_cselect_b32 s29, s30, s29
	s_cselect_b32 s8, s31, s8
	s_add_i32 s30, s29, 1
	s_cmp_ge_u32 s8, s28
	s_cselect_b32 s8, s30, s29
	s_xor_b32 s8, s8, s3
	s_sub_i32 s33, s8, s3
	s_mul_i32 s3, s33, s5
	s_sub_i32 s2, s2, s3
	s_add_i32 s8, s2, s4
.Lsn_join_10:
	v_readlane_b32 s4, v249, 38
	s_cmp_lg_u32 s4, 2
	s_cselect_b64 s[28:29], -1, 0
	s_mov_b64 s[2:3], -1
	s_and_b64 vcc, exec, s[28:29]
	s_cbranch_vccz .LBB0_1052
	v_readlane_b32 s2, v249, 18
	s_mul_hi_i32 s5, s8, s2
	s_mul_i32 s4, s8, s2
	s_mov_b64 s[2:3], 0

.LBB0_1073:
	s_ashr_i32 s5, s5, 3
	s_add_i32 s5, s46, s5
	s_abs_i32 s36, s5
	s_mul_hi_u32 s37, s36, s55
	s_mul_i32 s46, s37, s53
	s_ashr_i32 s9, s5, 31
	s_sub_i32 s36, s36, s46
	s_xor_b32 s9, s9, s52
	s_add_i32 s46, s37, 1
	s_sub_i32 s47, s36, s53
	s_cmp_ge_u32 s36, s53
	s_cselect_b32 s37, s46, s37
	s_cselect_b32 s36, s47, s36
	s_add_i32 s46, s37, 1
	s_cmp_ge_u32 s36, s53
	s_cselect_b32 s36, s46, s37
	s_xor_b32 s36, s36, s9
	s_sub_i32 s9, s36, s9
	s_lshl_b32 s36, s9, 3
	s_sub_i32 s37, s73, s36
	s_min_i32 s37, s37, 8
	s_cmp_lg_u32 s37, 8
	s_cbranch_scc1 .Lsn_slow_11
	s_mul_i32 s9, s9, s51
	s_sub_i32 s5, s5, s9
	s_and_b32 s98, s5, 7
	s_ashr_i32 s90, s5, 3
	s_add_i32 s91, s98, s36
	s_branch .Lsn_join_11
.Lsn_slow_11:
	s_abs_i32 s47, s37
	v_cvt_f32_u32_e32 v0, s47
	s_sub_i32 s48, 0, s47
	s_mul_i32 s9, s9, s51
	s_sub_i32 s5, s5, s9
	v_rcp_iflag_f32_e32 v0, v0
	s_abs_i32 s46, s5
	s_xor_b32 s9, s5, s37
	s_ashr_i32 s9, s9, 31
	v_mul_f32_e32 v0, 0x4f7ffffe, v0
	v_cvt_u32_f32_e32 v0, v0
	s_nop 0
	v_readfirstlane_b32 s49, v0
	s_mul_i32 s48, s48, s49
	s_mul_hi_u32 s48, s49, s48
	s_add_i32 s49, s49, s48
	s_mul_hi_u32 s48, s46, s49
	s_mul_i32 s49, s48, s47
	s_sub_i32 s46, s46, s49
	s_add_i32 s49, s48, 1
	s_sub_i32 s54, s46, s47
	s_cmp_ge_u32 s46, s47
	s_cselect_b32 s48, s49, s48
	s_cselect_b32 s46, s54, s46
	s_add_i32 s49, s48, 1
	s_cmp_ge_u32 s46, s47
	s_cselect_b32 s46, s49, s48
	s_xor_b32 s46, s46, s9
	s_sub_i32 s90, s46, s9
	s_mul_i32 s9, s90, s37
	s_sub_i32 s5, s5, s9
	s_add_i32 s91, s5, s36
.Lsn_join_11:
	s_mov_b64 s[46:47], -1
	s_and_b64 vcc, exec, s[28:29]
	s_cbranch_vccz .LBB0_1077
	v_readlane_b32 s5, v249, 18
	s_mul_hi_i32 s37, s91, s5
	s_mul_i32 s36, s91, s5
	s_cbranch_execz .LBB0_1078

.LBB0_1103:
	s_ashr_i32 s4, s6, 3
	v_readlane_b32 s6, v249, 30
	s_lshl_b32 s50, s6, 3
	s_abs_i32 s52, s50
	v_cvt_f32_u32_e32 v0, s52
	s_sub_i32 s7, 0, s52
	s_add_i32 s4, s8, s4
	s_bfe_i32 s51, s6, 0x1001c
	v_rcp_iflag_f32_e32 v0, v0
	s_abs_i32 s6, s4
	s_ashr_i32 s5, s4, 31
	s_xor_b32 s5, s5, s51
	v_mul_f32_e32 v0, 0x4f7ffffe, v0
	v_cvt_u32_f32_e32 v0, v0
	s_nop 0
	v_readfirstlane_b32 s53, v0
	s_mul_i32 s7, s7, s53
	s_mul_hi_u32 s7, s53, s7
	s_add_i32 s53, s53, s7
	s_mul_hi_u32 s7, s6, s53
	s_mul_i32 s8, s7, s52
	s_sub_i32 s6, s6, s8
	s_add_i32 s8, s7, 1
	s_sub_i32 s9, s6, s52
	s_cmp_ge_u32 s6, s52
	s_cselect_b32 s7, s8, s7
	s_cselect_b32 s6, s9, s6
	s_add_i32 s8, s7, 1
	s_cmp_ge_u32 s6, s52
	s_cselect_b32 s6, s8, s7
	s_xor_b32 s6, s6, s5
	s_sub_i32 s5, s6, s5
	s_lshl_b32 s6, s5, 3
	s_sub_i32 s7, s73, s6
	s_min_i32 s7, s7, 8
	s_cmp_lg_u32 s7, 8
	s_cbranch_scc1 .Lsn_slow_12
	s_mul_i32 s5, s5, s50
	s_sub_i32 s4, s4, s5
	s_and_b32 s98, s4, 7
	s_ashr_i32 s54, s4, 3
	s_add_i32 s55, s98, s6
	s_branch .Lsn_join_12
.Lsn_slow_12:
	s_abs_i32 s9, s7
	v_cvt_f32_u32_e32 v0, s9
	s_sub_i32 s21, 0, s9
	s_mul_i32 s5, s5, s50
	s_sub_i32 s4, s4, s5
	v_rcp_iflag_f32_e32 v0, v0
	s_abs_i32 s8, s4
	s_xor_b32 s5, s4, s7
	s_ashr_i32 s5, s5, 31
	v_mul_f32_e32 v0, 0x4f7ffffe, v0
	v_cvt_u32_f32_e32 v0, v0
	s_nop 0
	v_readfirstlane_b32 s23, v0
	s_mul_i32 s21, s21, s23
	s_mul_hi_u32 s21, s23, s21
	s_add_i32 s23, s23, s21
	s_mul_hi_u32 s21, s8, s23
	s_mul_i32 s23, s21, s9
	s_sub_i32 s8, s8, s23
	s_add_i32 s23, s21, 1
	s_sub_i32 s26, s8, s9
	s_cmp_ge_u32 s8, s9
	s_cselect_b32 s21, s23, s21
	s_cselect_b32 s8, s26, s8
	s_add_i32 s23, s21, 1
	s_cmp_ge_u32 s8, s9
	s_cselect_b32 s8, s23, s21
	s_xor_b32 s8, s8, s5
	s_sub_i32 s54, s8, s5
	s_mul_i32 s5, s54, s7
	s_sub_i32 s4, s4, s5
	s_add_i32 s55, s4, s6
.Lsn_join_12:
	v_readlane_b32 s4, v249, 38
	s_cmp_lg_u32 s4, 2
	s_cselect_b64 s[6:7], -1, 0
	s_mov_b64 s[26:27], -1
	s_and_b64 vcc, exec, s[6:7]
	s_cbranch_vccz .LBB0_1105
	v_readlane_b32 s4, v249, 18
	s_mul_hi_i32 s5, s55, s4
	s_mul_i32 s4, s55, s4
	s_mov_b64 s[26:27], 0

.LBB0_1126:
	s_ashr_i32 s25, s25, 3
	s_add_i32 s25, s40, s25
	s_abs_i32 s38, s25
	s_mul_hi_u32 s39, s38, s53
	s_mul_i32 s40, s39, s52
	s_ashr_i32 s37, s25, 31
	s_sub_i32 s38, s38, s40
	s_xor_b32 s37, s37, s51
	s_add_i32 s40, s39, 1
	s_sub_i32 s41, s38, s52
	s_cmp_ge_u32 s38, s52
	s_cselect_b32 s39, s40, s39
	s_cselect_b32 s38, s41, s38
	s_add_i32 s40, s39, 1
	s_cmp_ge_u32 s38, s52
	s_cselect_b32 s38, s40, s39
	s_xor_b32 s38, s38, s37
	s_sub_i32 s37, s38, s37
	s_lshl_b32 s38, s37, 3
	s_sub_i32 s39, s73, s38
	s_min_i32 s39, s39, 8
	s_cmp_lg_u32 s39, 8
	s_cbranch_scc1 .Lsn_slow_13
	s_mul_i32 s37, s37, s50
	s_sub_i32 s25, s25, s37
	s_and_b32 s98, s25, 7
	s_ashr_i32 s37, s25, 3
	s_add_i32 s91, s98, s38
	s_branch .Lsn_join_13
.Lsn_slow_13:
	s_abs_i32 s41, s39
	v_cvt_f32_u32_e32 v0, s41
	s_sub_i32 s46, 0, s41
	s_mul_i32 s37, s37, s50
	s_sub_i32 s25, s25, s37
	v_rcp_iflag_f32_e32 v0, v0
	s_abs_i32 s40, s25
	s_xor_b32 s37, s25, s39
	s_ashr_i32 s37, s37, 31
	v_mul_f32_e32 v0, 0x4f7ffffe, v0
	v_cvt_u32_f32_e32 v0, v0
	s_nop 0
	v_readfirstlane_b32 s47, v0
	s_mul_i32 s46, s46, s47
	s_mul_hi_u32 s46, s47, s46
	s_add_i32 s47, s47, s46
	s_mul_hi_u32 s46, s40, s47
	s_mul_i32 s47, s46, s41
	s_sub_i32 s40, s40, s47
	s_add_i32 s47, s46, 1
	s_sub_i32 s58, s40, s41
	s_cmp_ge_u32 s40, s41
	s_cselect_b32 s46, s47, s46
	s_cselect_b32 s40, s58, s40
	s_add_i32 s47, s46, 1
	s_cmp_ge_u32 s40, s41
	s_cselect_b32 s40, s47, s46
	s_xor_b32 s40, s40, s37
	s_sub_i32 s37, s40, s37
	s_mul_i32 s39, s37, s39
	s_sub_i32 s25, s25, s39
	s_add_i32 s91, s25, s38
.Lsn_join_13:
	s_mov_b64 s[40:41], -1
	s_and_b64 vcc, exec, s[6:7]
	s_cbranch_vccz .LBB0_1130
	v_readlane_b32 s10, v249, 18
	s_mul_hi_i32 s39, s91, s10
	s_mul_i32 s38, s91, s10
	s_cbranch_execz .LBB0_1131
